# code placement: uniform +16-byte shift of the whole kernel body (four s_nop at entry)
# speedup vs baseline: 1.0027x; 1.0012x over previous
; #define LAS __attribute__((address_space(3)))
; __global__ void __launch_bounds__(NWAVES * 64, 2) hybrid_fwd(Args args) {
;     extern __shared__ __attribute__((aligned(16))) unsigned char lds_raw[];
;     LAS unsigned char* lds = (LAS unsigned char*)lds_raw;
;     volatile LAS unsigned* MISC = (volatile LAS unsigned*)(lds + MISC_OFF);
;     const int tid = threadIdx.x, wave = __builtin_amdgcn_readfirstlane(tid >> 6);
;     const int G = gridDim.x, bx = blockIdx.x;
;     const int vcu = (G % 8 == 0) ? (bx % 8) * (G / 8) + bx / 8 : bx;
_Z10hybrid_fwd4Args:
	s_nop 0
	s_nop 0
	s_nop 0
	s_nop 0
	s_load_dword s64, s[0:1], 0xd8
	v_readfirstlane_b32 s51, v0
	v_writelane_b32 v249, s2, 0
	s_mov_b32 s65, s2
	s_waitcnt lgkmcnt(0)
	s_and_b32 s4, s64, 7
	s_cmp_eq_u32 s4, 0
	s_cselect_b64 s[10:11], -1, 0
	s_cmp_lg_u32 s4, 0
	s_cbranch_scc1 .LBB0_2
	v_readlane_b32 s2, v249, 0
	s_ashr_i32 s5, s2, 31
	s_lshr_b32 s5, s5, 29
	s_add_i32 s5, s2, s5
	s_and_b32 s6, s5, -8
	s_ashr_i32 s4, s64, 3
	s_sub_i32 s6, s2, s6
	s_mul_i32 s4, s4, s6
	s_ashr_i32 s5, s5, 3
	s_add_i32 s65, s4, s5
